# LDS-read software pipelining (4-deep, counted lgkmcnt) in M4 HGRN2/GLA and M6 HGRN2-FULL state-update MFMA sections
# speedup vs baseline: 1.0029x; 1.0029x over previous
; #define LAS __attribute__((address_space(3)))
; template <int TYPE, bool FULL>
; __device__ __forceinline__ void la_segment(const Frame& F, int item, const bf16* P, const float* GG, const float* LBl, const float* gn, float* SLOC, float* LDT, const float* SIN, bf16* Y) {
;     ...
;         { bf16x8 bv[NVT][2];
; #pragma unroll
;           for (int vt = 0; vt < NVT; ++vt)
; #pragma unroll
;               for (int ks = 0; ks < 2; ++ks) bv[vt][ks] = *(const LAS bf16x8*)(L + LA_VT + ((w * NVT + vt) * 16 + l15) * TS + (32 * ks + 8 * g4) * 2);
; #pragma unroll
;           for (int dt = 0; dt < 8; ++dt) { const f32x4 dec = *(const LAS f32x4*)(L + LA_DEC + (dt * 16 + 4 * g4) * 4);
;               const bf16x8 a0 = *(const LAS bf16x8*)(L + LA_KHT + (dt * 16 + l15) * TS + (8 * g4) * 2), a1 = *(const LAS bf16x8*)(L + LA_KHT + (dt * 16 + l15) * TS + (32 + 8 * g4) * 2);
; #pragma unroll
;               for (int vt = 0; vt < NVT; ++vt) { f32x4 sv = S[vt][dt] * dec; sv = __builtin_amdgcn_mfma_f32_16x16x32_bf16(a0, bv[vt][0], sv, 0, 0, 0); S[vt][dt] = __builtin_amdgcn_mfma_f32_16x16x32_bf16(a1, bv[vt][1], sv, 0, 0, 0); } } }
.LBB0_1579:
	v_add_u32_e32 v70, 0, v56
	s_waitcnt lgkmcnt(0)
	s_barrier
	v_add_u32_e32 v82, 0x22e00, v70
	v_pk_add_f32 v[44:45], v[44:45], v[36:37]
	ds_read_b128 v[36:39], v60
	ds_read_b128 v[40:43], v60 offset:64
	ds_read_b128 v[196:199], v82
	ds_read_b128 v[200:203], v61
	ds_read_b128 v[204:207], v61 offset:64
	ds_read_b128 v[208:211], v82 offset:64
	ds_read_b128 v[212:215], v61 offset:2304
	ds_read_b128 v[216:219], v61 offset:2368
	ds_read_b128 v[220:223], v82 offset:128
	ds_read_b128 v[224:227], v61 offset:4608
	ds_read_b128 v[236:239], v61 offset:4672
	ds_read_b128 v[240:243], v82 offset:192
	ds_read_b128 v[244:247], v61 offset:6912
	ds_read_b128 v[248:251], v61 offset:6976
	s_add_i32 s21, s21, 64
	s_cmpk_eq_i32 s21, 0x400
	s_waitcnt lgkmcnt(9)
	v_pk_mul_f32 v[2:3], v[2:3], v[196:197]
	v_pk_mul_f32 v[4:5], v[4:5], v[198:199]
	s_nop 1
	v_mfma_f32_16x16x32_bf16 v[2:5], v[200:203], v[36:39], v[2:5]
	v_mfma_f32_16x16x32_bf16 v[2:5], v[204:207], v[40:43], v[2:5]
	ds_read_b128 v[196:199], v82 offset:256
	ds_read_b128 v[200:203], v61 offset:9216
	ds_read_b128 v[204:207], v61 offset:9280
	s_waitcnt lgkmcnt(9)
	v_pk_mul_f32 v[30:31], v[30:31], v[208:209]
	v_pk_mul_f32 v[32:33], v[32:33], v[210:211]
	s_nop 1
	v_mfma_f32_16x16x32_bf16 v[30:33], v[212:215], v[36:39], v[30:33]
	v_mfma_f32_16x16x32_bf16 v[30:33], v[216:219], v[40:43], v[30:33]
	ds_read_b128 v[208:211], v82 offset:320
	ds_read_b128 v[212:215], v61 offset:11520
	ds_read_b128 v[216:219], v61 offset:11584
	s_waitcnt lgkmcnt(9)
	v_pk_mul_f32 v[22:23], v[22:23], v[220:221]
	v_pk_mul_f32 v[24:25], v[24:25], v[222:223]
	s_nop 1
	v_mfma_f32_16x16x32_bf16 v[22:25], v[224:227], v[36:39], v[22:25]
	v_mfma_f32_16x16x32_bf16 v[22:25], v[236:239], v[40:43], v[22:25]
	ds_read_b128 v[220:223], v82 offset:384
	ds_read_b128 v[224:227], v61 offset:13824
	ds_read_b128 v[236:239], v61 offset:13888
	s_waitcnt lgkmcnt(9)
	v_pk_mul_f32 v[26:27], v[26:27], v[240:241]
	v_pk_mul_f32 v[28:29], v[28:29], v[242:243]
	s_nop 1
	v_mfma_f32_16x16x32_bf16 v[26:29], v[244:247], v[36:39], v[26:29]
	v_mfma_f32_16x16x32_bf16 v[26:29], v[248:251], v[40:43], v[26:29]
	ds_read_b128 v[240:243], v82 offset:448
	ds_read_b128 v[244:247], v61 offset:16128
	ds_read_b128 v[248:251], v61 offset:16192
	s_waitcnt lgkmcnt(9)
	v_pk_mul_f32 v[18:19], v[18:19], v[196:197]
	v_pk_mul_f32 v[20:21], v[20:21], v[198:199]
	s_nop 1
	v_mfma_f32_16x16x32_bf16 v[18:21], v[200:203], v[36:39], v[18:21]
	v_mfma_f32_16x16x32_bf16 v[18:21], v[204:207], v[40:43], v[18:21]
	s_waitcnt lgkmcnt(6)
	v_pk_mul_f32 v[10:11], v[10:11], v[208:209]
	v_pk_mul_f32 v[12:13], v[12:13], v[210:211]
	s_nop 1
	v_mfma_f32_16x16x32_bf16 v[10:13], v[212:215], v[36:39], v[10:13]
	v_mfma_f32_16x16x32_bf16 v[10:13], v[216:219], v[40:43], v[10:13]
	s_waitcnt lgkmcnt(3)
	v_pk_mul_f32 v[6:7], v[6:7], v[220:221]
	v_pk_mul_f32 v[8:9], v[8:9], v[222:223]
	s_nop 1
	v_mfma_f32_16x16x32_bf16 v[6:9], v[224:227], v[36:39], v[6:9]
	v_mfma_f32_16x16x32_bf16 v[6:9], v[236:239], v[40:43], v[6:9]
	s_waitcnt lgkmcnt(0)
	v_pk_mul_f32 v[14:15], v[14:15], v[240:241]
	v_pk_mul_f32 v[16:17], v[16:17], v[242:243]
	s_nop 1
	v_mfma_f32_16x16x32_bf16 v[14:17], v[244:247], v[36:39], v[14:17]
	v_mfma_f32_16x16x32_bf16 v[14:17], v[248:251], v[40:43], v[14:17]
	s_cbranch_scc1 .LBB0_1584

; #define LAS __attribute__((address_space(3)))
; template <int TYPE, bool FULL>
; __device__ __forceinline__ void la_segment(const Frame& F, int item, const bf16* P, const float* GG, const float* LBl, const float* gn, float* SLOC, float* LDT, const float* SIN, bf16* Y) {
;     ...
;         { bf16x8 bv[NVT][2];
; #pragma unroll
;           for (int vt = 0; vt < NVT; ++vt)
; #pragma unroll
;               for (int ks = 0; ks < 2; ++ks) bv[vt][ks] = *(const LAS bf16x8*)(L + LA_VT + ((w * NVT + vt) * 16 + l15) * TS + (32 * ks + 8 * g4) * 2);
; #pragma unroll
;           for (int dt = 0; dt < 8; ++dt) { const f32x4 dec = *(const LAS f32x4*)(L + LA_DEC + (dt * 16 + 4 * g4) * 4);
;               const bf16x8 a0 = *(const LAS bf16x8*)(L + LA_KHT + (dt * 16 + l15) * TS + (8 * g4) * 2), a1 = *(const LAS bf16x8*)(L + LA_KHT + (dt * 16 + l15) * TS + (32 + 8 * g4) * 2);
; #pragma unroll
;               for (int vt = 0; vt < NVT; ++vt) { f32x4 sv = S[vt][dt] * dec; sv = __builtin_amdgcn_mfma_f32_16x16x32_bf16(a0, bv[vt][0], sv, 0, 0, 0); S[vt][dt] = __builtin_amdgcn_mfma_f32_16x16x32_bf16(a1, bv[vt][1], sv, 0, 0, 0); } } }
.LBB0_1589:
	v_add_u32_e32 v136, 0, v127
	s_waitcnt lgkmcnt(0)
	s_barrier
	v_add_u32_e32 v148, 0x22e00, v136
	v_pk_add_f32 v[106:107], v[106:107], v[68:69]
	ds_read_b128 v[80:83], v132
	ds_read_b128 v[76:79], v132 offset:64
	ds_read_b128 v[68:71], v132 offset:2304
	ds_read_b128 v[72:75], v132 offset:2368
	ds_read_b128 v[196:199], v148
	ds_read_b128 v[200:203], v133
	ds_read_b128 v[204:207], v133 offset:64
	ds_read_b128 v[208:211], v148 offset:64
	ds_read_b128 v[212:215], v133 offset:2304
	ds_read_b128 v[216:219], v133 offset:2368
	ds_read_b128 v[220:223], v148 offset:128
	ds_read_b128 v[224:227], v133 offset:4608
	ds_read_b128 v[236:239], v133 offset:4672
	ds_read_b128 v[240:243], v148 offset:192
	ds_read_b128 v[244:247], v133 offset:6912
	ds_read_b128 v[248:251], v133 offset:6976
	s_add_i32 s11, s11, 64
	s_cmpk_eq_i32 s11, 0x200
	s_waitcnt lgkmcnt(9)
	v_pk_mul_f32 v[2:3], v[2:3], v[196:197]
	v_pk_mul_f32 v[4:5], v[4:5], v[198:199]
	v_pk_mul_f32 v[36:37], v[36:37], v[196:197]
	v_pk_mul_f32 v[38:39], v[38:39], v[198:199]
	s_nop 1
	v_mfma_f32_16x16x32_bf16 v[2:5], v[200:203], v[80:83], v[2:5]
	v_mfma_f32_16x16x32_bf16 v[36:39], v[200:203], v[68:71], v[36:39]
	v_mfma_f32_16x16x32_bf16 v[2:5], v[204:207], v[76:79], v[2:5]
	v_mfma_f32_16x16x32_bf16 v[36:39], v[204:207], v[72:75], v[36:39]
	ds_read_b128 v[196:199], v148 offset:256
	ds_read_b128 v[200:203], v133 offset:9216
	ds_read_b128 v[204:207], v133 offset:9280
	s_waitcnt lgkmcnt(9)
	v_pk_mul_f32 v[64:65], v[64:65], v[208:209]
	v_pk_mul_f32 v[66:67], v[66:67], v[210:211]
	v_pk_mul_f32 v[30:31], v[30:31], v[208:209]
	v_pk_mul_f32 v[32:33], v[32:33], v[210:211]
	s_nop 1
	v_mfma_f32_16x16x32_bf16 v[64:67], v[212:215], v[80:83], v[64:67]
	v_mfma_f32_16x16x32_bf16 v[30:33], v[212:215], v[68:71], v[30:33]
	v_mfma_f32_16x16x32_bf16 v[64:67], v[216:219], v[76:79], v[64:67]
	v_mfma_f32_16x16x32_bf16 v[30:33], v[216:219], v[72:75], v[30:33]
	ds_read_b128 v[208:211], v148 offset:320
	ds_read_b128 v[212:215], v133 offset:11520
	ds_read_b128 v[216:219], v133 offset:11584
	s_waitcnt lgkmcnt(9)
	v_pk_mul_f32 v[56:57], v[56:57], v[220:221]
	v_pk_mul_f32 v[58:59], v[58:59], v[222:223]
	v_pk_mul_f32 v[26:27], v[26:27], v[220:221]
	v_pk_mul_f32 v[28:29], v[28:29], v[222:223]
	s_nop 1
	v_mfma_f32_16x16x32_bf16 v[56:59], v[224:227], v[80:83], v[56:59]
	v_mfma_f32_16x16x32_bf16 v[26:29], v[224:227], v[68:71], v[26:29]
	v_mfma_f32_16x16x32_bf16 v[56:59], v[236:239], v[76:79], v[56:59]
	v_mfma_f32_16x16x32_bf16 v[26:29], v[236:239], v[72:75], v[26:29]
	ds_read_b128 v[220:223], v148 offset:384
	ds_read_b128 v[224:227], v133 offset:13824
	ds_read_b128 v[236:239], v133 offset:13888
	s_waitcnt lgkmcnt(9)
	v_pk_mul_f32 v[60:61], v[60:61], v[240:241]
	v_pk_mul_f32 v[62:63], v[62:63], v[242:243]
	v_pk_mul_f32 v[22:23], v[22:23], v[240:241]
	v_pk_mul_f32 v[24:25], v[24:25], v[242:243]
	s_nop 1
	v_mfma_f32_16x16x32_bf16 v[60:63], v[244:247], v[80:83], v[60:63]
	v_mfma_f32_16x16x32_bf16 v[22:25], v[244:247], v[68:71], v[22:25]
	v_mfma_f32_16x16x32_bf16 v[60:63], v[248:251], v[76:79], v[60:63]
	v_mfma_f32_16x16x32_bf16 v[22:25], v[248:251], v[72:75], v[22:25]
	ds_read_b128 v[240:243], v148 offset:448
	ds_read_b128 v[244:247], v133 offset:16128
	ds_read_b128 v[248:251], v133 offset:16192
	s_waitcnt lgkmcnt(9)
	v_pk_mul_f32 v[48:49], v[48:49], v[196:197]
	v_pk_mul_f32 v[50:51], v[50:51], v[198:199]
	v_pk_mul_f32 v[18:19], v[18:19], v[196:197]
	v_pk_mul_f32 v[20:21], v[20:21], v[198:199]
	s_nop 1
	v_mfma_f32_16x16x32_bf16 v[48:51], v[200:203], v[80:83], v[48:51]
	v_mfma_f32_16x16x32_bf16 v[18:21], v[200:203], v[68:71], v[18:21]
	v_mfma_f32_16x16x32_bf16 v[48:51], v[204:207], v[76:79], v[48:51]
	v_mfma_f32_16x16x32_bf16 v[18:21], v[204:207], v[72:75], v[18:21]
	s_waitcnt lgkmcnt(6)
	v_pk_mul_f32 v[52:53], v[52:53], v[208:209]
	v_pk_mul_f32 v[54:55], v[54:55], v[210:211]
	v_pk_mul_f32 v[10:11], v[10:11], v[208:209]
	v_pk_mul_f32 v[12:13], v[12:13], v[210:211]
	s_nop 1
	v_mfma_f32_16x16x32_bf16 v[52:55], v[212:215], v[80:83], v[52:55]
	v_mfma_f32_16x16x32_bf16 v[10:13], v[212:215], v[68:71], v[10:13]
	v_mfma_f32_16x16x32_bf16 v[52:55], v[216:219], v[76:79], v[52:55]
	v_mfma_f32_16x16x32_bf16 v[10:13], v[216:219], v[72:75], v[10:13]
	s_waitcnt lgkmcnt(3)
	v_pk_mul_f32 v[40:41], v[40:41], v[220:221]
	v_pk_mul_f32 v[42:43], v[42:43], v[222:223]
	v_pk_mul_f32 v[6:7], v[6:7], v[220:221]
	v_pk_mul_f32 v[8:9], v[8:9], v[222:223]
	s_nop 1
	v_mfma_f32_16x16x32_bf16 v[40:43], v[224:227], v[80:83], v[40:43]
	v_mfma_f32_16x16x32_bf16 v[6:9], v[224:227], v[68:71], v[6:9]
	v_mfma_f32_16x16x32_bf16 v[40:43], v[236:239], v[76:79], v[40:43]
	v_mfma_f32_16x16x32_bf16 v[6:9], v[236:239], v[72:75], v[6:9]
	s_waitcnt lgkmcnt(0)
	v_pk_mul_f32 v[44:45], v[44:45], v[240:241]
	v_pk_mul_f32 v[46:47], v[46:47], v[242:243]
	v_pk_mul_f32 v[14:15], v[14:15], v[240:241]
	v_pk_mul_f32 v[16:17], v[16:17], v[242:243]
	s_nop 1
	v_mfma_f32_16x16x32_bf16 v[44:47], v[244:247], v[80:83], v[44:47]
	v_mfma_f32_16x16x32_bf16 v[14:17], v[244:247], v[68:71], v[14:17]
	v_mfma_f32_16x16x32_bf16 v[44:47], v[248:251], v[76:79], v[44:47]
	v_mfma_f32_16x16x32_bf16 v[14:17], v[248:251], v[72:75], v[14:17]
	s_cbranch_scc1 .LBB0_1594

; #define GAS __attribute__((address_space(1)))
; #define LAS __attribute__((address_space(3)))
; #define LA_BAR() do { asm volatile("s_waitcnt lgkmcnt(0)" ::: "memory"); __builtin_amdgcn_s_barrier(); asm volatile("" ::: "memory"); } while (0)
; template <int TYPE, bool FULL>
; __device__ __forceinline__ void la_segment(const Frame& F, int item, const bf16* P, const float* GG, const float* LBl, const float* gn, float* SLOC, float* LDT, const float* SIN, bf16* Y) {
;     ...
;             for (int I2 = 0; I2 < 4; ++I2)
; #pragma unroll
;                 for (int vt = 0; vt < NVT; ++vt) gwv[vt][I2] = *(const GAS v2u*)(P + (size_t)(m0 + 16 * I2 + l15) * PW + goff + (w * NVT + vt) * 16 + 4 * g4);
;         }
;         { bf16x8 bv[NVT][2];
; #pragma unroll
;           for (int vt = 0; vt < NVT; ++vt)
; #pragma unroll
;               for (int ks = 0; ks < 2; ++ks) bv[vt][ks] = *(const LAS bf16x8*)(L + LA_VT + ((w * NVT + vt) * 16 + l15) * TS + (32 * ks + 8 * g4) * 2);
; #pragma unroll
;           for (int dt = 0; dt < 8; ++dt) { const f32x4 dec = *(const LAS f32x4*)(L + LA_DEC + (dt * 16 + 4 * g4) * 4);
;               const bf16x8 a0 = *(const LAS bf16x8*)(L + LA_KHT + (dt * 16 + l15) * TS + (8 * g4) * 2), a1 = *(const LAS bf16x8*)(L + LA_KHT + (dt * 16 + l15) * TS + (32 + 8 * g4) * 2);
; #pragma unroll
;               for (int vt = 0; vt < NVT; ++vt) { f32x4 sv = S[vt][dt] * dec; sv = __builtin_amdgcn_mfma_f32_16x16x32_bf16(a0, bv[vt][0], sv, 0, 0, 0); S[vt][dt] = __builtin_amdgcn_mfma_f32_16x16x32_bf16(a1, bv[vt][1], sv, 0, 0, 0); } } }
;         if (FULL) {
;             LA_BAR();
.LBB0_1764:
	s_or_b64 exec, exec, s[60:61]
	s_add_i32 s60, s70, s10
	v_lshl_add_u32 v34, s60, 6, v115
	s_waitcnt lgkmcnt(0)
	v_mov_b64_e32 v[56:57], s[78:79]
	v_mad_u64_u32 v[58:59], s[60:61], v34, s95, v[56:57]
	s_lshl_b64 s[60:61], s[26:27], 1
	s_nop 0
	v_lshl_add_u64 v[58:59], v[58:59], 0, s[60:61]
	v_mov_b32_e32 v77, v35
	v_lshl_add_u64 v[58:59], v[58:59], 0, v[76:77]
	v_add_co_u32_e32 v58, vcc, 0x4000, v58
	v_or_b32_e32 v78, 16, v34
	s_nop 0
	v_addc_co_u32_e32 v59, vcc, 0, v59, vcc
	global_load_dwordx2 v[82:83], v[58:59], off
	v_mad_u64_u32 v[58:59], s[64:65], v78, s95, v[56:57]
	v_lshl_add_u64 v[58:59], v[58:59], 0, s[60:61]
	v_lshl_add_u64 v[58:59], v[58:59], 0, v[76:77]
	v_add_co_u32_e32 v58, vcc, 0x4000, v58
	v_or_b32_e32 v68, 32, v34
	s_nop 0
	v_addc_co_u32_e32 v59, vcc, 0, v59, vcc
	global_load_dwordx2 v[80:81], v[58:59], off
	v_mad_u64_u32 v[58:59], s[64:65], v68, s95, v[56:57]
	v_lshl_add_u64 v[58:59], v[58:59], 0, s[60:61]
	v_or_b32_e32 v64, 48, v34
	v_lshl_add_u64 v[58:59], v[58:59], 0, v[76:77]
	v_mad_u64_u32 v[56:57], s[64:65], v64, s95, v[56:57]
	v_add_co_u32_e32 v58, vcc, 0x4000, v58
	v_lshl_add_u64 v[56:57], v[56:57], 0, s[60:61]
	s_nop 0
	v_addc_co_u32_e32 v59, vcc, 0, v59, vcc
	v_lshl_add_u64 v[56:57], v[56:57], 0, v[76:77]
	v_add_co_u32_e32 v56, vcc, 0x4000, v56
	v_add_u32_e32 v77, 0x22e00, v72
	s_nop 0
	v_addc_co_u32_e32 v57, vcc, 0, v57, vcc
	global_load_dwordx2 v[70:71], v[58:59], off
	global_load_dwordx2 v[66:67], v[56:57], off
	ds_read_b128 v[60:63], v128
	ds_read_b128 v[56:59], v128 offset:64
	ds_read_b128 v[196:199], v77
	ds_read_b128 v[200:203], v124
	ds_read_b128 v[204:207], v124 offset:64
	ds_read_b128 v[208:211], v77 offset:64
	ds_read_b128 v[212:215], v124 offset:2304
	ds_read_b128 v[216:219], v124 offset:2368
	ds_read_b128 v[220:223], v77 offset:128
	ds_read_b128 v[224:227], v124 offset:4608
	ds_read_b128 v[236:239], v124 offset:4672
	ds_read_b128 v[240:243], v77 offset:192
	ds_read_b128 v[244:247], v124 offset:6912
	ds_read_b128 v[248:251], v124 offset:6976
	s_mov_b32 s60, 0x358637bd
	s_brev_b32 s64, 60
	v_mov_b32_e32 v79, v35
	v_mov_b32_e32 v69, v35
	v_lshlrev_b64 v[68:69], 11, v[68:69]
	v_lshl_add_u64 v[68:69], v[74:75], 0, v[68:69]
	v_mov_b32_e32 v65, v35
	s_waitcnt lgkmcnt(9)
	v_pk_mul_f32 v[4:5], v[4:5], v[198:199]
	v_pk_mul_f32 v[2:3], v[2:3], v[196:197]
	s_nop 1
	v_mfma_f32_16x16x32_bf16 v[2:5], v[200:203], v[60:63], v[2:5]
	v_mfma_f32_16x16x32_bf16 v[2:5], v[204:207], v[56:59], v[2:5]
	ds_read_b128 v[196:199], v77 offset:256
	ds_read_b128 v[200:203], v124 offset:9216
	ds_read_b128 v[204:207], v124 offset:9280
	s_cmp_lg_u32 s62, 16
	s_mov_b32 s70, s62
	s_waitcnt lgkmcnt(9)
	v_pk_mul_f32 v[6:7], v[6:7], v[208:209]
	v_pk_mul_f32 v[8:9], v[8:9], v[210:211]
	s_nop 1
	v_mfma_f32_16x16x32_bf16 v[6:9], v[212:215], v[60:63], v[6:9]
	v_mfma_f32_16x16x32_bf16 v[6:9], v[216:219], v[56:59], v[6:9]
	ds_read_b128 v[208:211], v77 offset:320
	ds_read_b128 v[212:215], v124 offset:11520
	ds_read_b128 v[216:219], v124 offset:11584
	s_waitcnt lgkmcnt(9)
	v_pk_mul_f32 v[10:11], v[10:11], v[220:221]
	v_pk_mul_f32 v[12:13], v[12:13], v[222:223]
	s_nop 1
	v_mfma_f32_16x16x32_bf16 v[10:13], v[224:227], v[60:63], v[10:13]
	v_mfma_f32_16x16x32_bf16 v[10:13], v[236:239], v[56:59], v[10:13]
	ds_read_b128 v[220:223], v77 offset:384
	ds_read_b128 v[224:227], v124 offset:13824
	ds_read_b128 v[236:239], v124 offset:13888
	s_waitcnt lgkmcnt(9)
	v_pk_mul_f32 v[14:15], v[14:15], v[240:241]
	v_pk_mul_f32 v[16:17], v[16:17], v[242:243]
	s_nop 1
	v_mfma_f32_16x16x32_bf16 v[14:17], v[244:247], v[60:63], v[14:17]
	v_mfma_f32_16x16x32_bf16 v[14:17], v[248:251], v[56:59], v[14:17]
	ds_read_b128 v[240:243], v77 offset:448
	ds_read_b128 v[244:247], v124 offset:16128
	ds_read_b128 v[248:251], v124 offset:16192
	s_waitcnt lgkmcnt(9)
	v_pk_mul_f32 v[18:19], v[18:19], v[196:197]
	v_pk_mul_f32 v[20:21], v[20:21], v[198:199]
	s_nop 1
	v_mfma_f32_16x16x32_bf16 v[18:21], v[200:203], v[60:63], v[18:21]
	v_mfma_f32_16x16x32_bf16 v[18:21], v[204:207], v[56:59], v[18:21]
	s_waitcnt lgkmcnt(6)
	v_pk_mul_f32 v[22:23], v[22:23], v[208:209]
	v_pk_mul_f32 v[24:25], v[24:25], v[210:211]
	s_nop 1
	v_mfma_f32_16x16x32_bf16 v[22:25], v[212:215], v[60:63], v[22:25]
	v_mfma_f32_16x16x32_bf16 v[22:25], v[216:219], v[56:59], v[22:25]
	s_waitcnt lgkmcnt(3)
	v_pk_mul_f32 v[26:27], v[26:27], v[220:221]
	v_pk_mul_f32 v[28:29], v[28:29], v[222:223]
	s_nop 1
	v_mfma_f32_16x16x32_bf16 v[26:29], v[224:227], v[60:63], v[26:29]
	v_mfma_f32_16x16x32_bf16 v[26:29], v[236:239], v[56:59], v[26:29]
	s_waitcnt lgkmcnt(0)
	s_nop 1
	s_waitcnt lgkmcnt(0)
	s_barrier
; #define GAS __attribute__((address_space(1)))
; #define LAS __attribute__((address_space(3)))
; __device__ __forceinline__ unsigned pk2(float lo, float hi) { f32x2_t v = {lo, hi}; bf16x2_t b = __builtin_convertvector(v, bf16x2_t); return __builtin_bit_cast(unsigned, b); }
; __device__ __forceinline__ float blo(unsigned w) { return __uint_as_float(w << 16); }
; __device__ __forceinline__ float bhi(unsigned w) { return __uint_as_float(w & 0xffff0000u); }
; __device__ __forceinline__ float sigm(float x) { return frcp(1.0f + __builtin_amdgcn_exp2f(-1.44269504089f * x)); }
; template <int TYPE, bool FULL>
; __device__ __forceinline__ void la_segment(const Frame& F, int item, const bf16* P, const float* GG, const float* LBl, const float* gn, float* SLOC, float* LDT, const float* SIN, bf16* Y) {
;     ...
;               for (int vt = 0; vt < NVT; ++vt) { f32x4 sv = S[vt][dt] * dec; sv = __builtin_amdgcn_mfma_f32_16x16x32_bf16(a0, bv[vt][0], sv, 0, 0, 0); S[vt][dt] = __builtin_amdgcn_mfma_f32_16x16x32_bf16(a1, bv[vt][1], sv, 0, 0, 0); } } }
;         if (FULL) {
;             LA_BAR();
; #pragma unroll
;             for (int I2 = 0; I2 < 4; ++I2) { float tot = 0.f;
; #pragma unroll
;                 for (int ww = 0; ww < 8; ++ww) tot += *(const LAS float*)(L + LA_NRM + (ww * 64 + 16 * I2 + l15) * 4);
;                 const float rstd = rsqrtf(tot * (1.f / DV) + EPS); const size_t m = (size_t)(m0 + 16 * I2 + l15);
; #pragma unroll
;                 for (int vt = 0; vt < NVT; ++vt) { const int col = (w * NVT + vt) * 16 + 4 * g4; const v2u gw = gwv[vt][I2]; const f32x4 gg = gnv[vt]; f32x4 o; if (TYPE == 0) { const v2u ob = *(const LAS v2u*)(L + LA_KP + (16 * I2 + l15) * OBS + col * 2); o = (f32x4){blo(ob.x), bhi(ob.x), blo(ob.y), bhi(ob.y)}; } else o = oacc[vt][I2];
;                     const float g0 = blo(gw.x), g1 = bhi(gw.x), g2 = blo(gw.y), g3 = bhi(gw.y);
;                     float a0, a1, a2, a3; if (TYPE == 0) { a0 = g0 * sigm(g0); a1 = g1 * sigm(g1); a2 = g2 * sigm(g2); a3 = g3 * sigm(g3); } else { a0 = sigm(g0); a1 = sigm(g1); a2 = sigm(g2); a3 = sigm(g3); }
;                     *(GAS v2u*)(Y + m * 1024 + h * DV + col) = (v2u){pk2(o.x * rstd * gg.x * a0, o.y * rstd * gg.y * a1), pk2(o.z * rstd * gg.z * a2, o.w * rstd * gg.w * a3)}; } }
	s_waitcnt lgkmcnt(2)
	v_pk_mul_f32 v[30:31], v[30:31], v[240:241]
	v_pk_mul_f32 v[32:33], v[32:33], v[242:243]
	s_waitcnt lgkmcnt(1)
	s_nop 0
	v_mfma_f32_16x16x32_bf16 v[30:33], v[244:247], v[60:63], v[30:33]
	s_waitcnt vmcnt(3)
	v_lshlrev_b32_e32 v60, 16, v83
	v_and_b32_e32 v62, 0xffff0000, v83
	s_waitcnt lgkmcnt(0)
	v_mfma_f32_16x16x32_bf16 v[30:33], v[248:251], v[56:59], v[30:33]
	v_add_u32_e32 v56, 0x24000, v126
	ds_read_b32 v57, v56
	v_add_u32_e32 v56, 0x24100, v126
	ds_read_b32 v59, v56
	v_add_u32_e32 v56, 0x24200, v126
	ds_read_b32 v61, v56
	v_add_u32_e32 v56, 0x24300, v126
	ds_read_b32 v63, v56
	v_add_u32_e32 v56, 0x24400, v126
	ds_read_b32 v85, v56
	v_add_u32_e32 v56, 0x24500, v126
	ds_read_b32 v87, v56
	v_add_u32_e32 v56, 0x24600, v126
	ds_read_b32 v89, v56
	v_add_u32_e32 v56, 0x24700, v126
	ds_read_b32 v91, v56
	v_lshlrev_b32_e32 v56, 16, v82
	v_mul_f32_e32 v56, 0xbfb8aa3b, v56
	v_exp_f32_e32 v56, v56
	v_and_b32_e32 v58, 0xffff0000, v82
	v_lshlrev_b64 v[140:141], 11, v[34:35]
	v_add_u32_e32 v34, 0x24040, v126
	v_add_f32_e32 v56, 1.0, v56
	v_rcp_f32_e32 v82, v56
	v_mul_f32_e32 v56, 0xbfb8aa3b, v58
	v_exp_f32_e32 v56, v56
	v_lshl_add_u64 v[140:141], v[74:75], 0, v[140:141]
	v_add_f32_e32 v56, 1.0, v56
	v_rcp_f32_e32 v83, v56
	v_mul_f32_e32 v56, 0xbfb8aa3b, v60
	v_exp_f32_e32 v56, v56
	s_nop 0
	v_add_f32_e32 v56, 1.0, v56
	v_rcp_f32_e32 v138, v56
	v_mul_f32_e32 v56, 0xbfb8aa3b, v62
	v_exp_f32_e32 v56, v56
	s_nop 0
	v_add_f32_e32 v56, 1.0, v56
	v_rcp_f32_e32 v139, v56
	ds_read_b32 v56, v34
	v_add_u32_e32 v34, 0x24140, v126
	ds_read_b32 v58, v34
	v_add_u32_e32 v34, 0x24240, v126
	ds_read_b32 v60, v34
	v_add_u32_e32 v34, 0x24340, v126
	ds_read_b32 v62, v34
	v_add_u32_e32 v34, 0x24440, v126
	ds_read_b32 v84, v34
	v_add_u32_e32 v34, 0x24540, v126
	ds_read_b32 v86, v34
	v_add_u32_e32 v34, 0x24640, v126
	s_waitcnt lgkmcnt(5)
	v_pk_add_f32 v[56:57], v[56:57], 0 op_sel_hi:[1,0]
	ds_read_b32 v88, v34
	v_add_u32_e32 v34, 0x24740, v126
	s_waitcnt lgkmcnt(5)
	v_pk_add_f32 v[56:57], v[56:57], v[58:59]
	ds_read_b32 v90, v34
	s_waitcnt lgkmcnt(5)
	v_pk_add_f32 v[56:57], v[56:57], v[60:61]
	s_waitcnt lgkmcnt(4)
	v_pk_add_f32 v[56:57], v[56:57], v[62:63]
	s_waitcnt lgkmcnt(3)
	v_pk_add_f32 v[56:57], v[56:57], v[84:85]
	s_waitcnt lgkmcnt(2)
	v_pk_add_f32 v[56:57], v[56:57], v[86:87]
	s_waitcnt lgkmcnt(1)
	v_pk_add_f32 v[56:57], v[56:57], v[88:89]
	s_waitcnt lgkmcnt(0)
	v_pk_add_f32 v[58:59], v[56:57], v[90:91]
	v_mov_b64_e32 v[56:57], s[60:61]
	v_pk_fma_f32 v[58:59], v[58:59], s[64:65], v[56:57] op_sel_hi:[1,0,0]
	s_nop 0
	v_mul_f32_e32 v34, 0x4b800000, v59
	v_cmp_gt_f32_e64 s[60:61], s90, v59
	v_cmp_gt_f32_e32 vcc, s90, v58
	s_nop 0
	v_cndmask_b32_e64 v34, v59, v34, s[60:61]
	v_rsq_f32_e32 v34, v34
	s_nop 0
	v_mul_f32_e32 v59, 0x45800000, v34
	v_cndmask_b32_e64 v34, v34, v59, s[60:61]
	v_pk_mul_f32 v[52:53], v[52:53], v[34:35] op_sel_hi:[1,0]
	v_pk_mul_f32 v[54:55], v[54:55], v[34:35] op_sel_hi:[1,0]
	v_mul_f32_e32 v34, 0x4b800000, v58
	v_cndmask_b32_e32 v34, v58, v34, vcc
	v_rsq_f32_e32 v34, v34
	v_pk_mul_f32 v[52:53], v[36:37], v[52:53]
	v_pk_mul_f32 v[54:55], v[38:39], v[54:55]
	v_pk_mul_f32 v[52:53], v[82:83], v[52:53]
	v_pk_mul_f32 v[54:55], v[138:139], v[54:55]
	v_cvt_pk_bf16_f32 v52, v52, v53
	v_cvt_pk_bf16_f32 v53, v54, v55
	global_store_dwordx2 v[140:141], v[52:53], off
	v_mul_f32_e32 v52, 0x45800000, v34
	v_cndmask_b32_e32 v34, v34, v52, vcc
	s_waitcnt vmcnt(3)
	v_lshlrev_b32_e32 v52, 16, v80
	v_and_b32_e32 v53, 0xffff0000, v80
	v_lshlrev_b32_e32 v54, 16, v81
	v_and_b32_e32 v55, 0xffff0000, v81
	v_mul_f32_e32 v52, 0xbfb8aa3b, v52
	v_mul_f32_e32 v53, 0xbfb8aa3b, v53
	v_mul_f32_e32 v54, 0xbfb8aa3b, v54
	v_mul_f32_e32 v55, 0xbfb8aa3b, v55
	v_exp_f32_e32 v52, v52
	v_exp_f32_e32 v53, v53
	v_exp_f32_e32 v54, v54
	v_exp_f32_e32 v55, v55
	v_add_f32_e32 v52, 1.0, v52
	v_add_f32_e32 v53, 1.0, v53
	v_add_f32_e32 v54, 1.0, v54
	v_add_f32_e32 v55, 1.0, v55
	v_rcp_f32_e32 v52, v52
	v_rcp_f32_e32 v53, v53
	v_rcp_f32_e32 v54, v54
	v_rcp_f32_e32 v55, v55
	v_pk_mul_f32 v[48:49], v[48:49], v[34:35] op_sel_hi:[1,0]
	v_pk_mul_f32 v[50:51], v[50:51], v[34:35] op_sel_hi:[1,0]
	v_pk_mul_f32 v[48:49], v[36:37], v[48:49]
	v_pk_mul_f32 v[50:51], v[38:39], v[50:51]
	v_pk_mul_f32 v[48:49], v[52:53], v[48:49]
	v_pk_mul_f32 v[50:51], v[54:55], v[50:51]
	v_cvt_pk_bf16_f32 v48, v48, v49
	v_cvt_pk_bf16_f32 v49, v50, v51
	v_lshlrev_b64 v[50:51], 11, v[78:79]
	v_lshl_add_u64 v[50:51], v[74:75], 0, v[50:51]
	v_add_u32_e32 v34, 0x24080, v126
	global_store_dwordx2 v[50:51], v[48:49], off
	ds_read_b32 v49, v34
	v_add_u32_e32 v34, 0x24180, v126
	ds_read_b32 v51, v34
	v_add_u32_e32 v34, 0x24280, v126
	ds_read_b32 v53, v34
	v_add_u32_e32 v34, 0x24380, v126
	ds_read_b32 v55, v34
	v_add_u32_e32 v34, 0x24480, v126
	ds_read_b32 v59, v34
	v_add_u32_e32 v34, 0x24580, v126
	ds_read_b32 v61, v34
	v_add_u32_e32 v34, 0x24680, v126
	ds_read_b32 v63, v34
	v_add_u32_e32 v34, 0x24780, v126
	ds_read_b32 v79, v34
	s_waitcnt vmcnt(3)
; #define GAS __attribute__((address_space(1)))
; #define LAS __attribute__((address_space(3)))
; __device__ __forceinline__ unsigned pk2(float lo, float hi) { f32x2_t v = {lo, hi}; bf16x2_t b = __builtin_convertvector(v, bf16x2_t); return __builtin_bit_cast(unsigned, b); }
; __device__ __forceinline__ float blo(unsigned w) { return __uint_as_float(w << 16); }
; __device__ __forceinline__ float bhi(unsigned w) { return __uint_as_float(w & 0xffff0000u); }
; __device__ __forceinline__ float sigm(float x) { return frcp(1.0f + __builtin_amdgcn_exp2f(-1.44269504089f * x)); }
; template <int TYPE, bool FULL>
; __device__ __forceinline__ void la_segment(const Frame& F, int item, const bf16* P, const float* GG, const float* LBl, const float* gn, float* SLOC, float* LDT, const float* SIN, bf16* Y) {
;     ...
;             for (int I2 = 0; I2 < 4; ++I2) { float tot = 0.f;
; #pragma unroll
;                 for (int ww = 0; ww < 8; ++ww) tot += *(const LAS float*)(L + LA_NRM + (ww * 64 + 16 * I2 + l15) * 4);
;                 const float rstd = rsqrtf(tot * (1.f / DV) + EPS); const size_t m = (size_t)(m0 + 16 * I2 + l15);
; #pragma unroll
;                 for (int vt = 0; vt < NVT; ++vt) { const int col = (w * NVT + vt) * 16 + 4 * g4; const v2u gw = gwv[vt][I2]; const f32x4 gg = gnv[vt]; f32x4 o; if (TYPE == 0) { const v2u ob = *(const LAS v2u*)(L + LA_KP + (16 * I2 + l15) * OBS + col * 2); o = (f32x4){blo(ob.x), bhi(ob.x), blo(ob.y), bhi(ob.y)}; } else o = oacc[vt][I2];
;                     const float g0 = blo(gw.x), g1 = bhi(gw.x), g2 = blo(gw.y), g3 = bhi(gw.y);
;                     float a0, a1, a2, a3; if (TYPE == 0) { a0 = g0 * sigm(g0); a1 = g1 * sigm(g1); a2 = g2 * sigm(g2); a3 = g3 * sigm(g3); } else { a0 = sigm(g0); a1 = sigm(g1); a2 = sigm(g2); a3 = sigm(g3); }
;                     *(GAS v2u*)(Y + m * 1024 + h * DV + col) = (v2u){pk2(o.x * rstd * gg.x * a0, o.y * rstd * gg.y * a1), pk2(o.z * rstd * gg.z * a2, o.w * rstd * gg.w * a3)}; } }
	v_lshlrev_b32_e32 v34, 16, v70
	v_mul_f32_e32 v34, 0xbfb8aa3b, v34
	v_exp_f32_e32 v34, v34
	v_and_b32_e32 v48, 0xffff0000, v70
	v_lshlrev_b32_e32 v50, 16, v71
	v_and_b32_e32 v52, 0xffff0000, v71
	v_add_f32_e32 v34, 1.0, v34
	v_rcp_f32_e32 v70, v34
	v_mul_f32_e32 v34, 0xbfb8aa3b, v48
	v_exp_f32_e32 v34, v34
	s_nop 0
	v_add_f32_e32 v34, 1.0, v34
	v_rcp_f32_e32 v71, v34
	v_mul_f32_e32 v34, 0xbfb8aa3b, v50
	v_exp_f32_e32 v34, v34
	s_nop 0
	v_add_f32_e32 v34, 1.0, v34
	v_rcp_f32_e32 v80, v34
	v_mul_f32_e32 v34, 0xbfb8aa3b, v52
	v_exp_f32_e32 v34, v34
	s_nop 0
	v_add_f32_e32 v34, 1.0, v34
	v_rcp_f32_e32 v81, v34
	v_add_u32_e32 v34, 0x240c0, v126
	ds_read_b32 v48, v34
	v_add_u32_e32 v34, 0x241c0, v126
	ds_read_b32 v50, v34
	v_add_u32_e32 v34, 0x242c0, v126
	ds_read_b32 v52, v34
	v_add_u32_e32 v34, 0x243c0, v126
	ds_read_b32 v54, v34
	v_add_u32_e32 v34, 0x244c0, v126
	ds_read_b32 v58, v34
	v_add_u32_e32 v34, 0x245c0, v126
	ds_read_b32 v60, v34
	v_add_u32_e32 v34, 0x246c0, v126
	s_waitcnt lgkmcnt(5)
	v_pk_add_f32 v[48:49], v[48:49], 0 op_sel_hi:[1,0]
	ds_read_b32 v62, v34
	v_add_u32_e32 v34, 0x247c0, v126
	s_waitcnt lgkmcnt(5)
	v_pk_add_f32 v[48:49], v[48:49], v[50:51]
	ds_read_b32 v78, v34
	s_waitcnt lgkmcnt(5)
	v_pk_add_f32 v[48:49], v[48:49], v[52:53]
	s_waitcnt lgkmcnt(4)
	v_pk_add_f32 v[48:49], v[48:49], v[54:55]
	s_waitcnt lgkmcnt(3)
	v_pk_add_f32 v[48:49], v[48:49], v[58:59]
	s_waitcnt lgkmcnt(2)
	v_pk_add_f32 v[48:49], v[48:49], v[60:61]
	s_waitcnt lgkmcnt(1)
	v_pk_add_f32 v[48:49], v[48:49], v[62:63]
	s_waitcnt lgkmcnt(0)
	v_pk_add_f32 v[48:49], v[48:49], v[78:79]
	s_nop 0
	v_pk_fma_f32 v[48:49], v[48:49], s[64:65], v[56:57] op_sel_hi:[1,0,0]
	s_nop 0
	v_mul_f32_e32 v34, 0x4b800000, v49
	v_cmp_gt_f32_e64 s[60:61], s90, v49
	v_cmp_gt_f32_e32 vcc, s90, v48
	s_nop 0
	v_cndmask_b32_e64 v34, v49, v34, s[60:61]
	v_rsq_f32_e32 v34, v34
	s_nop 0
	v_mul_f32_e32 v49, 0x45800000, v34
	v_cndmask_b32_e64 v34, v34, v49, s[60:61]
	v_pk_mul_f32 v[44:45], v[44:45], v[34:35] op_sel_hi:[1,0]
	v_pk_mul_f32 v[46:47], v[46:47], v[34:35] op_sel_hi:[1,0]
	v_mul_f32_e32 v34, 0x4b800000, v48
	v_cndmask_b32_e32 v34, v48, v34, vcc
	v_rsq_f32_e32 v34, v34
	v_pk_mul_f32 v[44:45], v[36:37], v[44:45]
	v_pk_mul_f32 v[46:47], v[38:39], v[46:47]
	v_pk_mul_f32 v[44:45], v[70:71], v[44:45]
	v_pk_mul_f32 v[46:47], v[80:81], v[46:47]
	v_cvt_pk_bf16_f32 v44, v44, v45
	v_cvt_pk_bf16_f32 v45, v46, v47
	global_store_dwordx2 v[68:69], v[44:45], off
	v_mul_f32_e32 v44, 0x45800000, v34
	v_cndmask_b32_e32 v34, v34, v44, vcc
	s_waitcnt vmcnt(3)
	v_lshlrev_b32_e32 v44, 16, v66
	v_and_b32_e32 v45, 0xffff0000, v66
	v_lshlrev_b32_e32 v46, 16, v67
	v_and_b32_e32 v47, 0xffff0000, v67
	v_mul_f32_e32 v44, 0xbfb8aa3b, v44
	v_mul_f32_e32 v45, 0xbfb8aa3b, v45
	v_mul_f32_e32 v46, 0xbfb8aa3b, v46
	v_mul_f32_e32 v47, 0xbfb8aa3b, v47
	v_exp_f32_e32 v44, v44
	v_exp_f32_e32 v45, v45
	v_exp_f32_e32 v46, v46
	v_exp_f32_e32 v47, v47
	v_add_f32_e32 v44, 1.0, v44
	v_add_f32_e32 v45, 1.0, v45
	v_add_f32_e32 v46, 1.0, v46
	v_add_f32_e32 v47, 1.0, v47
	v_rcp_f32_e32 v44, v44
	v_rcp_f32_e32 v45, v45
	v_rcp_f32_e32 v46, v46
	v_rcp_f32_e32 v47, v47
	v_pk_mul_f32 v[40:41], v[40:41], v[34:35] op_sel_hi:[1,0]
	v_pk_mul_f32 v[42:43], v[42:43], v[34:35] op_sel_hi:[1,0]
	v_pk_mul_f32 v[40:41], v[36:37], v[40:41]
	v_pk_mul_f32 v[42:43], v[38:39], v[42:43]
	v_pk_mul_f32 v[40:41], v[44:45], v[40:41]
	v_pk_mul_f32 v[42:43], v[46:47], v[42:43]
	v_cvt_pk_bf16_f32 v40, v40, v41
	v_cvt_pk_bf16_f32 v41, v42, v43
	v_lshlrev_b64 v[42:43], 11, v[64:65]
	v_lshl_add_u64 v[42:43], v[74:75], 0, v[42:43]
	global_store_dwordx2 v[42:43], v[40:41], off
	s_cbranch_scc0 .LBB0_1848
